# attention waves remapped (g = wid&3, th = wid>>2) so SIMD partners work on different token halves / tile classes
# baseline (speedup 1.0000x reference)
; #define LAS __attribute__((address_space(3)))
; __device__ __forceinline__ void attn_unit(LAS unsigned char* lds, const bf16* QKV, const bf16* KVC, bf16* O, const float* sink, int unit) {
;     const int tid = threadIdx.x, lane = tid & 63, wid = __builtin_amdgcn_readfirstlane(tid >> 6), r32 = lane & 31, hi = lane >> 5;
;     const int kvh = unit & 1, nb = (unit >> 1) & 127, b = unit >> 8;
;     const int g = wid >> 1, th = wid & 1, h = kvh * 4 + g;
;     const size_t t0 = (size_t)b * SEQ + (size_t)nb * 128;
;     bf16x8 qf[2][4];
; #pragma unroll
;     for (int qg = 0; qg < 2; ++qg)
; #pragma unroll
;         for (int ks = 0; ks < 4; ++ks) qf[qg][ks] = *(const bf16x8*)(QKV + (t0 + th * 64 + qg * 32 + r32) * NIN0 + h * 64 + ks * 16 + hi * 8);
;     LAS unsigned char* qlds = lds + 32768 + wid * 8192 + lane * 16;
; #pragma unroll
;     for (int qg = 0; qg < 2; ++qg)
; #pragma unroll
;         for (int ks = 0; ks < 4; ++ks) *(LAS bf16x8*)(qlds + (qg * 4 + ks) * 1024) = qf[qg][ks];
;     float mrun[2], lrun[2]; f32x16 o[2][2];
;     const float sk = sink[h] * LOG2E;
; #pragma unroll
;     for (int qg = 0; qg < 2; ++qg) { mrun[qg] = sk; lrun[qg] = hi ? 0.f : 1.f;
; #pragma unroll
;         for (int dg = 0; dg < 2; ++dg)
; #pragma unroll
;             for (int r = 0; r < 16; ++r) o[dg][qg][r] = 0.f; }
;     const int lkey = tid >> 3, lch = tid & 7;
;     const unsigned kw_off = (unsigned)(lkey * 128 + ((lch ^ (lkey & 7)) << 4));
;     const unsigned vw_off = (unsigned)(8192 + (lch >> 2) * 4096 + lkey * 64 + (lch & 3) * 16);
;     u32x4 kreg, vreg;
;     ...
;     LOAD_TILE(0);
.LBB0_501:
	v_readfirstlane_b32 s47, v206
	s_bfe_i32 s4, s8, 0x180007
	s_bfe_u32 s74, s47, 0x10008
	s_and_b32 s71, s8, 0x7f
	s_ashr_i32 s5, s4, 31
	s_lshl_b32 s75, s74, 6
	s_lshl_b64 s[40:41], s[4:5], 14
	s_lshl_b32 s73, s71, 7
	v_or_b32_e32 v199, s75, v141
	s_or_b32 s72, s40, s73
	s_and_b32 s12, s47, 0xc0
	s_lshl_b32 s12, s12, 1
	v_or_b32_e32 v200, 32, v199
	s_mov_b64 s[52:53], s[84:85]
	s_bfe_u32 s46, s47, 0x20006
	v_lshl_add_u64 v[18:19], v[138:139], 0, s[12:13]
	v_or_b32_e32 v166, s72, v199
	v_or_b32_e32 v164, s72, v200
	s_mov_b64 s[54:55], s[86:87]
	v_mad_u64_u32 v[14:15], s[42:43], v166, s56, v[18:19]
	v_mad_u64_u32 v[30:31], s[42:43], v164, s56, v[18:19]
	s_lshl_b32 s12, s46, 2
	v_readlane_b32 s76, v252, 1
	v_mad_i32_i24 v15, s41, v194, v15
	v_mad_i32_i24 v31, s41, v194, v31
	v_mov_b32_e32 v1, s12
	v_readlane_b32 s88, v252, 13
	v_readlane_b32 s89, v252, 14
	global_load_dwordx4 v[2:5], v[14:15], off
	global_load_dwordx4 v[6:9], v[14:15], off offset:32
	global_load_dwordx4 v[10:13], v[14:15], off offset:64
	s_nop 0
	global_load_dwordx4 v[14:17], v[14:15], off offset:96
	s_nop 0
	global_load_dwordx4 v[18:21], v[30:31], off
	global_load_dwordx4 v[22:25], v[30:31], off offset:32
	global_load_dwordx4 v[26:29], v[30:31], off offset:64
	s_nop 0
	global_load_dwordx4 v[30:33], v[30:31], off offset:96
	s_lshr_b32 s12, s47, 6
	global_load_dword v1, v1, s[88:89]
	s_lshl_b32 s42, s12, 13
	s_add_i32 s12, s73, 0xffffff80
	s_cmp_lg_u32 s71, 0
	v_mov_b32_e32 v167, s41
	v_add_u32_e32 v202, s42, v168
	s_cselect_b64 s[42:43], -1, 0
	s_cmp_eq_u32 s71, 0
	v_or_b32_e32 v162, s12, v140
	v_readlane_b32 s77, v252, 2
	v_readlane_b32 s78, v252, 3
	v_readlane_b32 s79, v252, 4
	v_readlane_b32 s80, v252, 5
	v_readlane_b32 s81, v252, 6
	v_readlane_b32 s82, v252, 7
	v_readlane_b32 s83, v252, 8
	v_readlane_b32 s84, v252, 9
	v_readlane_b32 s85, v252, 10
	v_readlane_b32 s86, v252, 11
	v_readlane_b32 s87, v252, 12
	v_readlane_b32 s90, v252, 15
	v_readlane_b32 s91, v252, 16
	s_waitcnt vmcnt(8)
	ds_write_b128 v202, v[2:5] offset:32768
	s_waitcnt vmcnt(7)
	ds_write_b128 v202, v[6:9] offset:33792
	s_waitcnt vmcnt(6)
	ds_write_b128 v202, v[10:13] offset:34816
	s_waitcnt vmcnt(5)
	ds_write_b128 v202, v[14:17] offset:35840
	s_waitcnt vmcnt(4)
	ds_write_b128 v202, v[18:21] offset:36864
	s_waitcnt vmcnt(3)
	ds_write_b128 v202, v[22:25] offset:37888
	s_waitcnt vmcnt(2)
	ds_write_b128 v202, v[26:29] offset:38912
	s_waitcnt vmcnt(1)
	ds_write_b128 v202, v[30:33] offset:39936
	s_cbranch_scc1 .LBB0_503
	v_or_b32_e32 v2, s12, v140
	v_mov_b32_e32 v3, v0
	v_lshl_add_u64 v[4:5], s[40:41], 0, v[2:3]
	v_mad_u64_u32 v[6:7], s[76:77], v4, s56, v[150:151]
	v_mad_i32_i24 v7, v5, s56, v7
	global_load_dwordx4 v[134:137], v[6:7], off offset:1024
	global_load_dwordx4 v[130:133], v[6:7], off offset:1280
	s_branch .LBB0_504

; __device__ __forceinline__ unsigned cvt_pk_bf16(float lo, float hi) { f32x2_t v = {lo, hi}; bf16x2_t b = __builtin_convertvector(v, bf16x2_t); return __builtin_bit_cast(unsigned, b); }
; #define LAS __attribute__((address_space(3)))
; __device__ __forceinline__ s16x4 vtr(const LAS char* p) { return __builtin_bit_cast(s16x4, __builtin_amdgcn_ds_read_tr16_b64_v4i16((LAS v4i16_t*)p)); }
; __device__ __forceinline__ void attn_unit(LAS unsigned char* lds, const bf16* QKV, const bf16* KVC, bf16* O, const float* sink, int unit) {
;     ...
;             float psa = 0.f, psb = 0.f;
; #pragma unroll
;             for (int kg = 0; kg < 2; ++kg)
; #pragma unroll
;                 for (int r = 0; r < 16; r += 2) { const float p0 = __builtin_amdgcn_exp2f(sacc[kg][qg][r]), p1 = __builtin_amdgcn_exp2f(sacc[kg][qg][r + 1]); sacc[kg][qg][r] = p0; sacc[kg][qg][r + 1] = p1; psa += p0; psb += p1; }
;             lrun[qg] += psa + psb;
; #pragma unroll
;             for (int kg = 0; kg < 2; ++kg)
; #pragma unroll
;                 for (int s = 0; s < 2; ++s) { u32x4 w;
;                     w.x = cvt_pk_bf16(sacc[kg][qg][8 * s + 0], sacc[kg][qg][8 * s + 1]); w.y = cvt_pk_bf16(sacc[kg][qg][8 * s + 2], sacc[kg][qg][8 * s + 3]);
;                     w.z = cvt_pk_bf16(sacc[kg][qg][8 * s + 4], sacc[kg][qg][8 * s + 5]); w.w = cvt_pk_bf16(sacc[kg][qg][8 * s + 6], sacc[kg][qg][8 * s + 7]);
;                     pf[kg][qg][s] = __builtin_bit_cast(bf16x8, w); }
;         }
; #pragma unroll
;         for (int dg = 0; dg < 2; ++dg)
; #pragma unroll
;             for (int kg = 0; kg < 2; ++kg)
; #pragma unroll
;                 for (int s = 0; s < 2; ++s) {
;                     const LAS char* vp = (const LAS char*)(buf + vr_base + dg * 4096 + (kg * 32 + 16 * s) * 64);
;                     const s16x4 lo = vtr(vp), hi4 = vtr(vp + 512);
;                     const bf16x8 vf = (bf16x8){lo[0], lo[1], lo[2], lo[3], hi4[0], hi4[1], hi4[2], hi4[3]};
; #pragma unroll
;                     for (int qg = 0; qg < 2; ++qg) o[dg][qg] = __builtin_amdgcn_mfma_f32_32x32x16_bf16(vf, pf[kg][qg][s], o[dg][qg], 0, 0, 0);
;                 }
.LBB0_530:
	v_exp_f32_e32 v114, v114
	v_exp_f32_e32 v115, v115
	v_exp_f32_e32 v116, v116
	v_exp_f32_e32 v117, v117
	v_exp_f32_e32 v118, v118
	v_exp_f32_e32 v119, v119
	v_exp_f32_e32 v120, v120
	v_exp_f32_e32 v121, v121
	v_add_f32_e32 v130, 0, v114
	v_add_f32_e32 v131, 0, v115
	v_add_f32_e32 v130, v116, v130
	v_add_f32_e32 v131, v117, v131
	v_add_f32_e32 v130, v118, v130
	v_add_f32_e32 v131, v119, v131
	v_add_f32_e32 v134, v120, v130
	v_add_f32_e32 v135, v121, v131
	v_exp_f32_e32 v205, v126
	v_exp_f32_e32 v207, v127
	v_exp_f32_e32 v208, v128
	v_exp_f32_e32 v209, v129
	v_exp_f32_e32 v210, v82
	v_exp_f32_e32 v211, v83
	v_exp_f32_e32 v212, v84
	v_exp_f32_e32 v213, v85
	v_exp_f32_e32 v216, v88
	v_exp_f32_e32 v217, v89
	v_exp_f32_e32 v218, v90
	v_exp_f32_e32 v219, v91
	v_exp_f32_e32 v220, v92
	ds_read_b64_tr_b16 v[82:83], v198 offset:24576
	ds_read_b64_tr_b16 v[84:85], v198 offset:25088
	v_exp_f32_e32 v221, v93
	v_cvt_pk_bf16_f32 v88, v118, v119
	v_cvt_pk_bf16_f32 v89, v120, v121
	ds_read_b64_tr_b16 v[90:91], v198 offset:25600
	ds_read_b64_tr_b16 v[92:93], v198 offset:26112
	ds_read_b64_tr_b16 v[118:119], v198 offset:26624
	ds_read_b64_tr_b16 v[120:121], v198 offset:27136
	ds_read_b64_tr_b16 v[126:127], v198 offset:27648
	ds_read_b64_tr_b16 v[128:129], v198 offset:28160
	ds_read_b64_tr_b16 v[130:131], v198 offset:28672
	ds_read_b64_tr_b16 v[132:133], v198 offset:29184
	v_exp_f32_e32 v136, v122
	v_exp_f32_e32 v137, v123
	v_exp_f32_e32 v203, v124
	v_exp_f32_e32 v204, v125
	v_exp_f32_e32 v214, v86
	v_exp_f32_e32 v215, v87
	v_cvt_pk_bf16_f32 v86, v114, v115
	v_cvt_pk_bf16_f32 v87, v116, v117
	v_add_f32_e32 v134, v136, v134
	v_add_f32_e32 v135, v137, v135
	s_waitcnt lgkmcnt(8)
	v_mfma_f32_32x32x16_bf16 v[50:65], v[82:85], v[86:89], v[50:65]
	v_add_f32_e32 v134, v203, v134
	v_cvt_pk_bf16_f32 v114, v136, v137
	v_cvt_pk_bf16_f32 v115, v203, v204
	v_add_f32_e32 v203, v204, v135
	v_add_f32_e32 v204, v205, v134
	ds_read_b64_tr_b16 v[134:135], v198 offset:29696
	ds_read_b64_tr_b16 v[136:137], v198 offset:30208
	v_cvt_pk_bf16_f32 v116, v205, v207
	s_waitcnt lgkmcnt(2)
	v_mfma_f32_32x32x16_bf16 v[34:49], v[130:133], v[86:89], v[34:49]
	v_cvt_pk_bf16_f32 v117, v208, v209
	v_add_f32_e32 v86, v207, v203
	v_add_f32_e32 v87, v208, v204
	v_add_f32_e32 v203, v209, v86
	v_add_f32_e32 v207, v210, v87
	ds_read_b64_tr_b16 v[86:87], v198 offset:30720
	ds_read_b64_tr_b16 v[88:89], v198 offset:31232
	v_cvt_pk_bf16_f32 v122, v210, v211
	v_mfma_f32_32x32x16_bf16 v[50:65], v[90:93], v[114:117], v[50:65]
	v_cvt_pk_bf16_f32 v123, v212, v213
	v_cvt_pk_bf16_f32 v124, v214, v215
	v_cvt_pk_bf16_f32 v125, v216, v217
	v_exp_f32_e32 v222, v94
	v_exp_f32_e32 v223, v95
	v_exp_f32_e32 v224, v96
	v_exp_f32_e32 v225, v97
	s_waitcnt lgkmcnt(2)
	v_mfma_f32_32x32x16_bf16 v[34:49], v[134:137], v[114:117], v[34:49]
	v_exp_f32_e32 v204, v98
	v_exp_f32_e32 v205, v99
	v_exp_f32_e32 v114, v100
	v_exp_f32_e32 v115, v101
	ds_read_b64_tr_b16 v[98:99], v198 offset:31744
	ds_read_b64_tr_b16 v[100:101], v198 offset:32256
	v_exp_f32_e32 v102, v102
	v_exp_f32_e32 v103, v103
	v_mfma_f32_32x32x16_bf16 v[50:65], v[118:121], v[122:125], v[50:65]
	v_exp_f32_e32 v104, v104
	v_exp_f32_e32 v105, v105
	v_cvt_pk_bf16_f32 v94, v218, v219
	v_cvt_pk_bf16_f32 v95, v220, v221
	v_cvt_pk_bf16_f32 v96, v222, v223
	v_cvt_pk_bf16_f32 v97, v224, v225
	v_exp_f32_e32 v106, v106
	s_waitcnt lgkmcnt(2)
	v_mfma_f32_32x32x16_bf16 v[34:49], v[86:89], v[122:125], v[34:49]
	v_exp_f32_e32 v107, v107
	v_exp_f32_e32 v108, v108
	v_exp_f32_e32 v109, v109
	v_exp_f32_e32 v110, v110
	v_exp_f32_e32 v111, v111
	v_exp_f32_e32 v112, v112
	v_exp_f32_e32 v113, v113
	v_mfma_f32_32x32x16_bf16 v[50:65], v[126:129], v[94:97], v[50:65]
	v_exp_f32_e32 v116, v70
	v_exp_f32_e32 v117, v71
	v_exp_f32_e32 v122, v72
	v_exp_f32_e32 v123, v73
	v_exp_f32_e32 v78, v78
	v_cvt_pk_bf16_f32 v72, v116, v117
	v_exp_f32_e32 v79, v79
	s_waitcnt lgkmcnt(0)
	v_mfma_f32_32x32x16_bf16 v[34:49], v[98:101], v[94:97], v[34:49]
	v_cvt_pk_bf16_f32 v94, v204, v205
	v_cvt_pk_bf16_f32 v95, v114, v115
	v_cvt_pk_bf16_f32 v96, v102, v103
	v_cvt_pk_bf16_f32 v97, v104, v105
	v_cvt_pk_bf16_f32 v73, v122, v123
	v_exp_f32_e32 v80, v80
	v_exp_f32_e32 v81, v81
	v_mfma_f32_32x32x16_bf16 v[18:33], v[82:85], v[94:97], v[18:33]
	v_exp_f32_e32 v82, v66
	v_exp_f32_e32 v83, v67
	v_exp_f32_e32 v84, v68
	v_exp_f32_e32 v85, v69
	v_cvt_pk_bf16_f32 v66, v106, v107
	v_cvt_pk_bf16_f32 v67, v108, v109
	v_cvt_pk_bf16_f32 v68, v110, v111
	v_mfma_f32_32x32x16_bf16 v[2:17], v[130:133], v[94:97], v[2:17]
	v_cvt_pk_bf16_f32 v69, v112, v113
	v_cvt_pk_bf16_f32 v70, v82, v83
	v_cvt_pk_bf16_f32 v71, v84, v85
	v_exp_f32_e32 v94, v74
	v_exp_f32_e32 v95, v75
	s_lshl_b32 s12, s73, 1
	s_mov_b32 s47, s13
	v_mfma_f32_32x32x16_bf16 v[18:33], v[90:93], v[66:69], v[18:33]
	v_add_f32_e32 v92, v211, v203
	v_add_f32_e32 v93, v212, v207
	v_add_f32_e32 v92, v213, v92
	v_add_f32_e32 v93, v214, v93
	v_add_f32_e32 v92, v215, v92
	v_add_f32_e32 v93, v216, v93
	v_add_f32_e32 v92, v217, v92
	v_mfma_f32_32x32x16_bf16 v[2:17], v[134:137], v[66:69], v[2:17]
	v_add_f32_e32 v66, v218, v93
	v_add_f32_e32 v67, v219, v92
	v_add_f32_e32 v66, v220, v66
	v_add_f32_e32 v67, v221, v67
	v_add_f32_e32 v66, v222, v66
	v_add_f32_e32 v67, v223, v67
	v_add_f32_e32 v66, v224, v66
	v_add_f32_e32 v67, v225, v67
	v_add_f32_e32 v66, v66, v67
	v_add_f32_e32 v68, v163, v66
	ds_bpermute_b32 v69, v185, v68
	v_pk_add_f32 v[66:67], v[204:205], 0 op_sel_hi:[1,0]
	v_mfma_f32_32x32x16_bf16 v[18:33], v[118:121], v[70:73], v[18:33]
	v_add_f32_e64 v66, v114, v66
	v_add_f32_e64 v67, v115, v67
	v_exp_f32_e32 v90, v76
	v_pk_add_f32 v[66:67], v[102:103], v[66:67]
	s_waitcnt lgkmcnt(0)
; __device__ __forceinline__ unsigned cvt_pk_bf16(float lo, float hi) { f32x2_t v = {lo, hi}; bf16x2_t b = __builtin_convertvector(v, bf16x2_t); return __builtin_bit_cast(unsigned, b); }
; __device__ __forceinline__ void attn_unit(LAS unsigned char* lds, const bf16* QKV, const bf16* KVC, bf16* O, const float* sink, int unit) {
;     const int tid = threadIdx.x, lane = tid & 63, wid = __builtin_amdgcn_readfirstlane(tid >> 6), r32 = lane & 31, hi = lane >> 5;
;     const int kvh = unit & 1, nb = (unit >> 1) & 127, b = unit >> 8;
;     const int g = wid >> 1, th = wid & 1, h = kvh * 4 + g;
;     const size_t t0 = (size_t)b * SEQ + (size_t)nb * 128;
;     bf16x8 qf[2][4];
; #pragma unroll
;     for (int qg = 0; qg < 2; ++qg)
; #pragma unroll
;         for (int ks = 0; ks < 4; ++ks) qf[qg][ks] = *(const bf16x8*)(QKV + (t0 + th * 64 + qg * 32 + r32) * NIN0 + h * 64 + ks * 16 + hi * 8);
;     ...
; #pragma unroll
;     for (int qg = 0; qg < 2; ++qg) {
;         const float lt = lrun[qg] + __shfl_xor(lrun[qg], 32); const float inv = 1.0f / lt;
;         bf16* op = O + (t0 + th * 64 + qg * 32 + r32) * D + h * 64 + 4 * hi;
; #pragma unroll
;         for (int dg = 0; dg < 2; ++dg)
; #pragma unroll
;             for (int rg = 0; rg < 4; ++rg) { u32x2 w; w.x = cvt_pk_bf16(o[dg][qg][4 * rg] * inv, o[dg][qg][4 * rg + 1] * inv); w.y = cvt_pk_bf16(o[dg][qg][4 * rg + 2] * inv, o[dg][qg][4 * rg + 3] * inv);
;                 *(u32x2*)(op + dg * 32 + 8 * rg) = w; }
;     }
;     __syncthreads();
	v_add_f32_e32 v68, v68, v69
	v_pk_add_f32 v[66:67], v[104:105], v[66:67]
	v_div_scale_f32 v69, s[4:5], v68, v68, 1.0
	v_pk_add_f32 v[66:67], v[106:107], v[66:67]
	v_mfma_f32_32x32x16_bf16 v[2:17], v[86:89], v[70:73], v[2:17]
	v_add_f32_e64 v66, v108, v66
	v_add_f32_e64 v67, v109, v67
	v_rcp_f32_e32 v70, v69
	v_pk_add_f32 v[66:67], v[110:111], v[66:67]
	v_exp_f32_e32 v91, v77
	v_pk_add_f32 v[66:67], v[112:113], v[66:67]
	v_fma_f32 v71, -v69, v70, 1.0
	v_pk_add_f32 v[66:67], v[82:83], v[66:67]
	v_fmac_f32_e32 v70, v71, v70
	v_pk_add_f32 v[66:67], v[84:85], v[66:67]
	v_div_scale_f32 v71, vcc, 1.0, v68, 1.0
	v_pk_add_f32 v[66:67], v[116:117], v[66:67]
	v_mul_f32_e32 v72, v71, v70
	v_pk_add_f32 v[66:67], v[122:123], v[66:67]
	v_fma_f32 v73, -v69, v72, v71
	v_pk_add_f32 v[66:67], v[94:95], v[66:67]
	v_fmac_f32_e32 v72, v73, v70
	v_pk_add_f32 v[66:67], v[90:91], v[66:67]
	v_fma_f32 v69, -v69, v72, v71
	v_pk_add_f32 v[66:67], v[78:79], v[66:67]
	v_div_fmas_f32 v69, v69, v70, v72
	v_pk_add_f32 v[66:67], v[80:81], v[66:67]
	v_div_fixup_f32 v68, v69, v68, 1.0
	v_add_f32_e32 v66, v66, v67
	v_add_f32_e32 v1, v1, v66
	v_lshl_add_u64 v[66:67], v[142:143], 0, s[12:13]
	v_lshlrev_b64 v[70:71], 11, v[166:167]
	v_pk_mul_f32 v[34:35], v[34:35], v[68:69] op_sel_hi:[1,0]
	v_pk_mul_f32 v[36:37], v[36:37], v[68:69] op_sel_hi:[1,0]
	v_lshl_add_u64 v[70:71], v[66:67], 0, v[70:71]
	v_cvt_pk_bf16_f32 v34, v34, v35
	v_cvt_pk_bf16_f32 v35, v36, v37
	global_store_dwordx2 v[70:71], v[34:35], off offset:64
	v_pk_mul_f32 v[34:35], v[38:39], v[68:69] op_sel_hi:[1,0]
	ds_bpermute_b32 v38, v185, v1
	v_pk_mul_f32 v[36:37], v[40:41], v[68:69] op_sel_hi:[1,0]
	v_cvt_pk_bf16_f32 v34, v34, v35
	v_cvt_pk_bf16_f32 v35, v36, v37
	global_store_dwordx2 v[70:71], v[34:35], off offset:80
	s_waitcnt lgkmcnt(0)
	v_add_f32_e32 v1, v1, v38
	v_div_scale_f32 v38, s[4:5], v1, v1, 1.0
	v_pk_mul_f32 v[34:35], v[42:43], v[68:69] op_sel_hi:[1,0]
	v_pk_mul_f32 v[36:37], v[44:45], v[68:69] op_sel_hi:[1,0]
	v_rcp_f32_e32 v39, v38
	v_cvt_pk_bf16_f32 v34, v34, v35
	v_cvt_pk_bf16_f32 v35, v36, v37
	global_store_dwordx2 v[70:71], v[34:35], off offset:96
	v_pk_mul_f32 v[34:35], v[46:47], v[68:69] op_sel_hi:[1,0]
	v_pk_mul_f32 v[36:37], v[48:49], v[68:69] op_sel_hi:[1,0]
	v_cvt_pk_bf16_f32 v74, v94, v95
	v_cvt_pk_bf16_f32 v75, v90, v91
	v_cvt_pk_bf16_f32 v76, v78, v79
	v_cvt_pk_bf16_f32 v77, v80, v81
	v_cvt_pk_bf16_f32 v34, v34, v35
	v_cvt_pk_bf16_f32 v35, v36, v37
	v_mfma_f32_32x32x16_bf16 v[18:33], v[126:129], v[74:77], v[18:33]
	global_store_dwordx2 v[70:71], v[34:35], off offset:112
	v_fma_f32 v34, -v38, v39, 1.0
	v_fmac_f32_e32 v39, v34, v39
	v_div_scale_f32 v34, vcc, 1.0, v1, 1.0
	v_mul_f32_e32 v35, v34, v39
	v_fma_f32 v36, -v38, v35, v34
	v_mfma_f32_32x32x16_bf16 v[2:17], v[98:101], v[74:77], v[2:17]
	v_fmac_f32_e32 v35, v36, v39
	v_fma_f32 v34, -v38, v35, v34
	v_div_fmas_f32 v34, v34, v39, v35
	v_div_fixup_f32 v34, v34, v1, 1.0
	v_lshlrev_b64 v[36:37], 11, v[164:165]
	v_pk_mul_f32 v[18:19], v[18:19], v[34:35] op_sel_hi:[1,0]
	v_pk_mul_f32 v[20:21], v[20:21], v[34:35] op_sel_hi:[1,0]
	v_lshl_add_u64 v[36:37], v[66:67], 0, v[36:37]
	v_cvt_pk_bf16_f32 v18, v18, v19
	v_cvt_pk_bf16_f32 v19, v20, v21
	global_store_dwordx2 v[36:37], v[18:19], off
	v_pk_mul_f32 v[18:19], v[22:23], v[34:35] op_sel_hi:[1,0]
	v_pk_mul_f32 v[20:21], v[24:25], v[34:35] op_sel_hi:[1,0]
	v_cvt_pk_bf16_f32 v18, v18, v19
	v_cvt_pk_bf16_f32 v19, v20, v21
	v_pk_mul_f32 v[2:3], v[2:3], v[34:35] op_sel_hi:[1,0]
	v_pk_mul_f32 v[4:5], v[4:5], v[34:35] op_sel_hi:[1,0]
	v_readfirstlane_b32 s12, v206
	v_pk_mul_f32 v[50:51], v[50:51], v[68:69] op_sel_hi:[1,0]
	v_pk_mul_f32 v[52:53], v[52:53], v[68:69] op_sel_hi:[1,0]
	global_store_dwordx2 v[36:37], v[18:19], off offset:16
	v_pk_mul_f32 v[18:19], v[26:27], v[34:35] op_sel_hi:[1,0]
	v_pk_mul_f32 v[20:21], v[28:29], v[34:35] op_sel_hi:[1,0]
	v_cvt_pk_bf16_f32 v2, v2, v3
	v_cvt_pk_bf16_f32 v3, v4, v5
	s_bfe_u32 s73, s12, 0x10008
	v_cvt_pk_bf16_f32 v50, v50, v51
	v_cvt_pk_bf16_f32 v51, v52, v53
	v_cvt_pk_bf16_f32 v18, v18, v19
	v_cvt_pk_bf16_f32 v19, v20, v21
	global_store_dwordx2 v[36:37], v[2:3], off offset:64
	v_pk_mul_f32 v[2:3], v[6:7], v[34:35] op_sel_hi:[1,0]
	v_pk_mul_f32 v[4:5], v[8:9], v[34:35] op_sel_hi:[1,0]
	s_bfe_u32 s75, s12, 0x20006
	s_lshl_b32 s74, s73, 6
	global_store_dwordx2 v[70:71], v[50:51], off
	v_pk_mul_f32 v[50:51], v[54:55], v[68:69] op_sel_hi:[1,0]
	v_pk_mul_f32 v[52:53], v[56:57], v[68:69] op_sel_hi:[1,0]
	global_store_dwordx2 v[36:37], v[18:19], off offset:32
	v_pk_mul_f32 v[18:19], v[30:31], v[34:35] op_sel_hi:[1,0]
	v_pk_mul_f32 v[20:21], v[32:33], v[34:35] op_sel_hi:[1,0]
	v_cvt_pk_bf16_f32 v2, v2, v3
	v_cvt_pk_bf16_f32 v3, v4, v5
	s_lshl_b32 s4, s75, 6
	v_or_b32_e32 v204, s74, v141
	v_cvt_pk_bf16_f32 v50, v50, v51
	v_cvt_pk_bf16_f32 v51, v52, v53
	v_cvt_pk_bf16_f32 v18, v18, v19
	v_cvt_pk_bf16_f32 v19, v20, v21
	global_store_dwordx2 v[36:37], v[2:3], off offset:80
	v_pk_mul_f32 v[2:3], v[10:11], v[34:35] op_sel_hi:[1,0]
	v_pk_mul_f32 v[4:5], v[12:13], v[34:35] op_sel_hi:[1,0]
	s_add_i32 s46, s4, 0x100
	v_or_b32_e32 v205, 32, v204
	global_store_dwordx2 v[70:71], v[50:51], off offset:16
	v_pk_mul_f32 v[50:51], v[58:59], v[68:69] op_sel_hi:[1,0]
	v_pk_mul_f32 v[52:53], v[60:61], v[68:69] op_sel_hi:[1,0]
	global_store_dwordx2 v[36:37], v[18:19], off offset:48
	v_cvt_pk_bf16_f32 v2, v2, v3
	v_cvt_pk_bf16_f32 v3, v4, v5
	v_lshl_add_u64 v[18:19], s[46:47], 1, v[138:139]
	v_or_b32_e32 v166, s72, v204
	v_or_b32_e32 v164, s72, v205
	v_cvt_pk_bf16_f32 v50, v50, v51
	v_cvt_pk_bf16_f32 v51, v52, v53
	global_store_dwordx2 v[36:37], v[2:3], off offset:96
	v_pk_mul_f32 v[2:3], v[14:15], v[34:35] op_sel_hi:[1,0]
	v_mad_u64_u32 v[14:15], s[4:5], v166, s56, v[18:19]
	s_mul_i32 s76, s41, 0xe00
	v_mad_u64_u32 v[30:31], s[4:5], v164, s56, v[18:19]
	global_store_dwordx2 v[70:71], v[50:51], off offset:32
	v_pk_mul_f32 v[50:51], v[62:63], v[68:69] op_sel_hi:[1,0]
	v_pk_mul_f32 v[52:53], v[64:65], v[68:69] op_sel_hi:[1,0]
	v_pk_mul_f32 v[4:5], v[16:17], v[34:35] op_sel_hi:[1,0]
	v_add_u32_e32 v15, s76, v15
	v_add_u32_e32 v31, s76, v31
	s_lshl_b32 s4, s75, 2
	v_readlane_b32 s76, v252, 1
	v_cvt_pk_bf16_f32 v50, v50, v51
	v_cvt_pk_bf16_f32 v51, v52, v53
	v_cvt_pk_bf16_f32 v2, v2, v3
	v_cvt_pk_bf16_f32 v3, v4, v5
	v_mov_b32_e32 v1, s4
	v_readlane_b32 s88, v252, 13
	v_readlane_b32 s89, v252, 14
	global_store_dwordx2 v[70:71], v[50:51], off offset:48
	global_store_dwordx2 v[36:37], v[2:3], off offset:112
	s_barrier
; #define LAS __attribute__((address_space(3)))
; __device__ __forceinline__ void attn_unit(LAS unsigned char* lds, const bf16* QKV, const bf16* KVC, bf16* O, const float* sink, int unit) {
;     ...
; #pragma unroll
;     for (int qg = 0; qg < 2; ++qg)
; #pragma unroll
;         for (int ks = 0; ks < 4; ++ks) qf[qg][ks] = *(const bf16x8*)(QKV + (t0 + th * 64 + qg * 32 + r32) * NIN0 + h * 64 + ks * 16 + hi * 8);
;     LAS unsigned char* qlds = lds + 32768 + wid * 8192 + lane * 16;
; #pragma unroll
;     for (int qg = 0; qg < 2; ++qg)
; #pragma unroll
;         for (int ks = 0; ks < 4; ++ks) *(LAS bf16x8*)(qlds + (qg * 4 + ks) * 1024) = qf[qg][ks];
;     float mrun[2], lrun[2]; f32x16 o[2][2];
;     const float sk = sink[h] * LOG2E;
; #pragma unroll
;     for (int qg = 0; qg < 2; ++qg) { mrun[qg] = sk; lrun[qg] = hi ? 0.f : 1.f;
; #pragma unroll
;         for (int dg = 0; dg < 2; ++dg)
; #pragma unroll
;             for (int r = 0; r < 16; ++r) o[dg][qg][r] = 0.f; }
;     const int lkey = tid >> 3, lch = tid & 7;
;     const unsigned kw_off = (unsigned)(lkey * 128 + ((lch ^ (lkey & 7)) << 4));
;     const unsigned vw_off = (unsigned)(8192 + (lch >> 2) * 4096 + lkey * 64 + (lch & 3) * 16);
;     u32x4 kreg, vreg;
;     ...
;     LOAD_TILE(0);
	global_load_dwordx4 v[2:5], v[14:15], off
	global_load_dwordx4 v[6:9], v[14:15], off offset:32
	global_load_dwordx4 v[10:13], v[14:15], off offset:64
	s_nop 0
	global_load_dwordx4 v[14:17], v[14:15], off offset:96
	s_nop 0
	global_load_dwordx4 v[18:21], v[30:31], off
	global_load_dwordx4 v[22:25], v[30:31], off offset:32
	global_load_dwordx4 v[26:29], v[30:31], off offset:64
	s_nop 0
	global_load_dwordx4 v[30:33], v[30:31], off offset:96
	s_lshr_b32 s4, s12, 6
	global_load_dword v1, v1, s[88:89] offset:16
	s_lshl_b32 s4, s4, 13
	v_mov_b32_e32 v167, s41
	v_add_u32_e32 v203, s4, v168
	s_andn2_b64 vcc, exec, s[42:43]
	v_readlane_b32 s77, v252, 2
	v_readlane_b32 s78, v252, 3
	v_readlane_b32 s79, v252, 4
	v_readlane_b32 s80, v252, 5
	v_readlane_b32 s81, v252, 6
	v_readlane_b32 s82, v252, 7
	v_readlane_b32 s83, v252, 8
	v_readlane_b32 s84, v252, 9
	v_readlane_b32 s85, v252, 10
	v_readlane_b32 s86, v252, 11
	v_readlane_b32 s87, v252, 12
	v_readlane_b32 s90, v252, 15
	v_readlane_b32 s91, v252, 16
	s_waitcnt vmcnt(8)
	ds_write_b128 v203, v[2:5] offset:32768
	s_waitcnt vmcnt(7)
	ds_write_b128 v203, v[6:9] offset:33792
	s_waitcnt vmcnt(6)
	ds_write_b128 v203, v[10:13] offset:34816
	s_waitcnt vmcnt(5)
	ds_write_b128 v203, v[14:17] offset:35840
	s_waitcnt vmcnt(4)
	ds_write_b128 v203, v[18:21] offset:36864
	s_waitcnt vmcnt(3)
	ds_write_b128 v203, v[22:25] offset:37888
	s_waitcnt vmcnt(2)
	ds_write_b128 v203, v[26:29] offset:38912
	s_waitcnt vmcnt(1)
	ds_write_b128 v203, v[30:33] offset:39936
	s_cbranch_vccnz .LBB0_532
	v_mov_b32_e32 v163, v0
	v_lshl_add_u64 v[2:3], s[40:41], 0, v[162:163]
	v_mad_u64_u32 v[4:5], s[4:5], v2, s56, v[150:151]
	v_mad_i32_i24 v5, v3, s56, v5
	global_load_dwordx4 v[134:137], v[4:5], off offset:1152
	global_load_dwordx4 v[130:133], v[4:5], off offset:1408
	s_branch .LBB0_533
